# S5 pass 2 on three waves (wave 3 two units, waves 7 and 6 one each): two of the three RWKV scan SIMDs unshared
# baseline (speedup 1.0000x reference)
; __device__ __forceinline__ int bidx() { int b = blockIdx.x; asm volatile("" : "+s"(b)); return b; }
; #define LAS __attribute__((address_space(3)))
; template <int PASS>
; __device__ __forceinline__ void s5_scan(const Params& p, int l, int widx, int nw, int beff, int nblk, int lane, LAS unsigned char* lds) {
;     if (widx < 0 || widx >= nw || beff < 0) return;
;     unsigned char* ws = p.ws;
;     LAS float* ub = (LAS float*)(lds + widx * 19456);
;     LAS float* xb = ub + 512;
;     LAS float* ct = xb + 16 * 132;
;     const float* ZS = (const float*)(ws + WS_ZS); const float* tab = (const float*)(ws + WS_S5TAB + (size_t)l * SZ_S5TAB);
;     float* XE = (float*)(ws + WS_XE);
;     float* YS = (float*)(ws + WS_YS); bf16_t* YSB = (bf16_t*)(ws + WS_YSB);
;     for (int u = widx * nblk + beff; u < 1024; u += nw * nblk) {
;         const int c = u & 15, g = (u >> 4) & 31, b = u >> 9; const int gn = g * 64 + lane;
; __global__ void __launch_bounds__(512, 2) mk_fwd(Params p) {
;     ...
;                 s5_scan<1>(p, l, wave - 4, 4, bidx(), gridDim.x, lane, lds);
;             } else if (s == 6 && PON(7)) {
;                 rwkv_scan<1>(p, l, wave, lane, lds);
;                 s5_scan<2>(p, l, (wave == 3) ? 0 : ((wave == 7) ? 1 : -1), 2, bidx(), gridDim.x, lane, lds + 24576);
.LBB0_324:
	s_setprio 0
	v_readlane_b32 s1, v254, 17
	s_cmp_eq_u32 s1, 7
	s_cselect_b32 s0, 1, -1
	s_cmp_eq_u32 s1, 6
	s_cselect_b32 s0, 2, s0
	s_cmp_lg_u32 s1, 3
	s_cselect_b32 s0, s0, 0
	s_mov_b32 s1, s2
	s_or_b32 s4, s1, s0
	s_cmp_lt_i32 s4, 0
	v_mov_b64_e32 v[196:197], v[142:143]
	v_mov_b32_e32 v143, v190
	v_mov_b32_e32 v192, 0xfcf
	v_not_b32_e32 v193, 63
	s_cbranch_scc1 .LBB0_356
	v_readlane_b32 s4, v253, 5
	s_mul_i32 s4, s0, s4
	s_add_i32 s6, s1, s4
	s_cmpk_gt_i32 s6, 0x3ff
	v_readlane_b32 s5, v253, 6
	s_cbranch_scc1 .LBB0_356
	s_mulk_i32 s0, 0x4c00
	v_readlane_b32 s4, v255, 18
	s_add_i32 s7, s0, 0
	s_lshl_b64 s[0:1], s[86:87], 15
	v_readlane_b32 s5, v255, 19
	v_readlane_b32 s8, v253, 17
	v_lshlrev_b32_e32 v0, 2, v201
	s_lshl_b64 s[4:5], s[4:5], 2
	v_readlane_b32 s10, v253, 19
	v_or_b32_e32 v44, s0, v201
	v_mov_b32_e32 v45, s1
	v_and_b32_e32 v46, 12, v0
	v_readlane_b32 s0, v251, 40
	v_readlane_b32 s11, v253, 20
	s_add_u32 s4, s10, s4
	v_lshlrev_b32_e32 v136, 2, v46
	v_readlane_b32 s1, v251, 41
	s_addc_u32 s5, s11, s5
	v_readlane_b32 s12, v253, 21
	v_lshl_add_u64 v[48:49], s[0:1], 0, v[136:137]
	s_add_i32 s0, s7, 0x6800
	s_add_i32 s1, s7, 0x8900
	v_and_b32_e32 v134, 15, v201
	v_lshrrev_b32_e32 v135, 4, v201
	v_mul_u32_u24_e32 v138, 0x210, v134
	v_lshl_add_u32 v138, v135, 4, v138
	v_lshl_add_u32 v135, v135, 6, v134
	v_add_u32_e32 v134, s0, v138
	v_lshl_add_u32 v135, v135, 2, s0
	v_lshl_add_u32 v138, v201, 4, s0
	v_readlane_b32 s13, v253, 22
	v_readlane_b32 s14, v253, 23
	v_readlane_b32 s15, v253, 24
	v_add_u32_e32 v72, s7, v0
	v_add_u32_e32 v73, s0, v0
	v_mov_b32_e32 v0, s1
	s_movk_i32 s1, 0x210
	v_readlane_b32 s9, v253, 18
	v_lshrrev_b32_e32 v65, 2, v201
	v_mad_u32_u24 v74, v46, s1, v0
	v_mov_b32_e32 v0, s0
	v_readlane_b32 s12, v253, 41
	v_lshlrev_b32_e32 v47, 1, v201
	v_lshlrev_b32_e32 v70, 4, v201
	v_lshlrev_b32_e32 v71, 6, v65
	v_lshl_add_u64 v[50:51], s[4:5], 0, v[136:137]
	s_add_i32 s8, s7, 0x6000
	v_mad_u32_u24 v75, v65, s1, v0
	s_mov_b32 s9, s6
	v_readlane_b32 s26, v253, 55
	v_readlane_b32 s27, v253, 56
	v_readlane_b32 s13, v253, 42
	v_readlane_b32 s14, v253, 43
	v_readlane_b32 s15, v253, 44
	v_readlane_b32 s16, v253, 45
	v_readlane_b32 s17, v253, 46
	v_readlane_b32 s18, v253, 47
	v_readlane_b32 s19, v253, 48
	v_readlane_b32 s20, v253, 49
	v_readlane_b32 s21, v253, 50
	v_readlane_b32 s22, v253, 51
	v_readlane_b32 s23, v253, 52
	v_readlane_b32 s24, v253, 53
	v_readlane_b32 s25, v253, 54
	s_branch .LBB0_328
.LBB0_327:
	v_readlane_b32 s0, v253, 7
	s_add_i32 s6, s6, s0
	s_add_i32 s9, s9, s0
	v_readlane_b32 s12, v253, 41
	s_cmpk_gt_i32 s6, 0x3ff
	v_readlane_b32 s26, v253, 55
	v_readlane_b32 s27, v253, 56
	v_readlane_b32 s13, v253, 42
	v_readlane_b32 s14, v253, 43
	v_readlane_b32 s15, v253, 44
	v_readlane_b32 s16, v253, 45
	v_readlane_b32 s17, v253, 46
	v_readlane_b32 s18, v253, 47
	v_readlane_b32 s19, v253, 48
	v_readlane_b32 s20, v253, 49
	v_readlane_b32 s21, v253, 50
	v_readlane_b32 s22, v253, 51
	v_readlane_b32 s23, v253, 52
	v_readlane_b32 s24, v253, 53
	v_readlane_b32 s25, v253, 54
	s_cbranch_scc1 .LBB0_356
